# v36 + every other group of 8 workgroups enters each GEMM phase s_sleep 18 (~0.7 us) later, de-phasing the LDS-DMA bursts inside each XCD
# speedup vs baseline: 1.0058x; 1.0058x over previous
; #define LAS __attribute__((address_space(3)))
; __device__ __forceinline__ int otid() { int t = threadIdx.x; asm volatile("" : "+v"(t)); return t; }
; __global__ void __launch_bounds__(NT, 2) fwd(Args args) {
;     extern __shared__ __attribute__((aligned(16))) unsigned char lds_raw[];
;     LAS unsigned char* lds = (LAS unsigned char*)lds_raw;
;     volatile LAS unsigned* MISC = (volatile LAS unsigned*)(lds + MISC_OFF);
;     const int tid = otid(), lane = tid & 63, wave = __builtin_amdgcn_readfirstlane(tid >> 6);
;     const int G = gridDim.x, bx = blockIdx.x;
;     const int vcu = (G % 8 == 0) ? (bx % 8) * (G / 8) + bx / 8 : bx;
_Z3fwd4Args:
	v_mov_b32_e32 v148, v0
	v_writelane_b32 v243, s2, 40
	s_load_dword s76, s[0:1], 0xb8
	v_ashrrev_i32_e32 v150, 6, v148
	s_mov_b32 s86, s2
	v_readfirstlane_b32 s2, v150
	s_nop 1
	v_writelane_b32 v242, s2, 0
	s_add_u32 s2, s0, 0xb8
	s_addc_u32 s3, s1, 0
	v_writelane_b32 v242, s2, 1
	s_nop 1
	v_writelane_b32 v242, s3, 2
	s_waitcnt lgkmcnt(0)
	s_and_b32 s2, s76, 7
	s_cmp_lg_u32 s2, 0
	s_mov_b32 s2, s86
	s_cbranch_scc1 .LBB0_2
	s_ashr_i32 s3, s86, 31
	s_lshr_b32 s3, s3, 29
	s_add_i32 s3, s86, s3
	s_and_b32 s4, s3, -8
	s_ashr_i32 s2, s76, 3
	s_sub_i32 s4, s86, s4
	s_mul_i32 s2, s2, s4
	s_ashr_i32 s3, s3, 3
	s_add_i32 s2, s2, s3

; #define REP(k) for (int rep_ = 0; rep_ < ((DUP) == (k) ? 2 : 1); ++rep_)
; #define PG8_STAGE(bufoff, gbase, voff) do { _Pragma("unroll") for (int _i = 0; _i < 2; ++_i) { unsigned keep_; \
;         asm volatile("s_mov_b32 %0, m0\n\ts_mov_b32 m0, %3\n\ts_nop 0\n\tglobal_load_lds_dwordx4 %1, %2\n\ts_mov_b32 m0, %0" \
;             : "=&s"(keep_) : "v"((voff)[_i]), "s"((const void*)(gbase)), "s"(ldsb0 + (unsigned)(bufoff) + (unsigned)(_i * 8192)) : "memory"); } } while (0)
; #define PG8_WAIT_V(n) asm volatile("s_waitcnt vmcnt(" #n ")" ::: "memory")
; #define PG8_BAR __builtin_amdgcn_s_barrier()
; template <class Epi, class Sched, bool ALIGN_EPI>
; __device__ __forceinline__ void gemm_phase(LAS unsigned char* lds, const Gemm g, const Sched& S, const Epi& E) {
;     ...
;     Unit cur, nxt; int ui = 0;
;     if (!S.next(0, cur)) return;
;     f32x4 acc[2][2][4][2];
; #pragma unroll
;     for (int a = 0; a < 2; ++a)
; #pragma unroll
;         for (int b = 0; b < 2; ++b)
; #pragma unroll
;             for (int m = 0; m < 4; ++m)
; #pragma unroll
;                 for (int n = 0; n < 2; ++n) acc[a][b][m][n] = (f32x4){0.f, 0.f, 0.f, 0.f};
;     bf16x8 At[4][2], B0[2][2], B1[2][2];
;     float pre[Epi::NPRE > 0 ? Epi::NPRE : 1];
;     if constexpr (Epi::NPRE > 0) E.preload(cur, wr, fr, pre);
;     const char* cA = (const char*)g.A + (size_t)cur.pm * tstepA + (size_t)cur.pn * g.a_koff * 2; const char* cB = (const char*)g.Bt + (size_t)cur.pn * tstepB;
;     PG8_STAGE(PG8_SB(0, 0), cB, voffB); PG8_STAGE(PG8_SB(0, 1), cB + hstepB, voffB); PG8_STAGE(PG8_SA(0, 0), cA, voffA); PG8_STAGE(PG8_SA(0, 1), cA + hstepA, voffA);
;     if (wr == 1) PG8_BAR;
;     PG8_WAIT_V(2); PG8_BAR;
;     PG8_STAGE(PG8_SB(1, 0), cB + kstep, voffB); PG8_STAGE(PG8_SA(1, 0), cA + kstep, voffA); PG8_STAGE(PG8_SB(1, 1), cB + hstepB + kstep, voffB);
;     PG8_WAIT_V(6); PG8_BAR;
; __global__ void __launch_bounds__(NT, 2) fwd(Args args) {
;     ...
;     xcd_barrier(bar);
;     REP(1) {
;         pg8::Gemm g{XB, WIN, DM, DM, DM, 0}; EpiIn E{ssq, UBF, out + O_POOLP, QB, KB, VB, out + O_FKP, out + O_FVP};
;         pg8::BalancedOrder S{2, bx, G}; pg8::gemm_phase<EpiIn, pg8::BalancedOrder, true>(lds, g, S, E);
.LBB0_99:
	s_or_b64 exec, exec, s[4:5]
	s_cmpk_lg_i32 s76, 0x100
	s_cselect_b64 s[20:21], -1, 0
	s_cmpk_gt_i32 s86, 0x1ff
	s_cselect_b64 s[18:19], -1, 0
	s_lshl_b32 s2, s86, 2
	s_and_b32 s4, s2, 24
	s_bfe_u32 s5, s86, 0x30003
	s_or_b32 s26, s4, s5
	s_and_b32 s2, s2, 4
	s_ashr_i32 s4, s86, 6
	s_ashr_i32 s24, s86, 5
	s_and_b32 s25, s86, 31
	s_add_i32 s27, s2, s4
	s_cmpk_eq_i32 s76, 0x100
	s_cselect_b64 s[22:23], -1, 0
	v_writelane_b32 v242, s22, 10
	s_mov_b64 s[10:11], s[0:1]
	s_mov_b64 s[12:13], s[0:1]
	v_writelane_b32 v242, s23, 11
	s_and_b64 s[22:23], s[22:23], exec
	s_mov_b64 s[14:15], s[0:1]
	s_mov_b64 s[6:7], s[0:1]
	s_mov_b64 s[16:17], s[0:1]
	s_mov_b64 s[4:5], s[0:1]
	s_mov_b64 s[8:9], s[0:1]
	s_mov_b64 s[28:29], s[0:1]
	s_mov_b64 s[30:31], s[0:1]
	s_mov_b64 s[34:35], s[0:1]
	s_waitcnt lgkmcnt(0)
	v_mov_b32_e32 v2, v0
	s_cselect_b32 s22, s27, s24
	s_cselect_b32 s60, s26, s25
	s_and_b64 s[18:19], s[20:21], s[18:19]
	s_barrier
	v_readlane_b32 s99, v243, 40
	s_nop 1
	s_bitcmp1_b32 s99, 3
	s_cbranch_scc0 .Lstg_0
	s_sleep 18
.Lstg_0:
	v_writelane_b32 v242, s27, 12
	v_readfirstlane_b32 s2, v2
	s_and_b64 vcc, exec, s[18:19]
	v_writelane_b32 v242, s26, 13
	s_cbranch_vccnz .LBB0_376
	v_bfe_i32 v4, v2, 27, 1
	v_lshlrev_b32_e32 v6, 4, v2
	v_lshrrev_b32_e32 v4, 22, v4
	v_add_u32_e32 v4, v6, v4
	v_and_b32_e32 v4, 0xfffffc00, v4
	v_sub_u32_e32 v4, v6, v4
	s_load_dwordx2 s[10:11], s[10:11], 0xb0
	s_nop 0
	s_load_dwordx2 s[12:13], s[12:13], 0xb0
	s_nop 0
	s_load_dwordx2 s[18:19], s[14:15], 0xb0
	s_nop 0
	s_load_dwordx2 s[14:15], s[6:7], 0xb0
	s_nop 0
	s_load_dwordx2 s[16:17], s[16:17], 0xa8
	v_ashrrev_i32_e32 v3, 31, v2
	v_lshrrev_b32_e32 v5, 4, v4
	s_waitcnt lgkmcnt(0)
	s_add_u32 s53, s10, 0x1d800000
	v_lshrrev_b32_e32 v3, 26, v3
	v_bitop3_b32 v5, v5, v4, 32 bitop3:0x6c
	v_ashrrev_i32_e32 v4, 31, v4
	s_addc_u32 s54, s11, 0
	v_add_u32_e32 v3, v2, v3
	v_lshrrev_b32_e32 v4, 26, v4
	s_add_u32 s55, s12, 0x100000
	v_ashrrev_i32_e32 v3, 6, v3
	v_add_u32_e32 v4, v5, v4
	s_addc_u32 s57, s13, 0
	v_lshlrev_b32_e32 v7, 3, v3
	v_ashrrev_i32_e32 v8, 6, v4
	v_lshlrev_b32_e32 v3, 5, v3
	s_add_u32 s10, s18, 0x10000
	v_and_b32_e32 v9, 32, v3
	v_mul_i32_i24_e32 v3, 64, v8
	s_addc_u32 s11, s19, 0
	s_ashr_i32 s25, s2, 8
	v_sub_u32_e32 v3, v5, v3
	v_mov_b32_e32 v10, 1
	s_load_dwordx2 s[18:19], s[4:5], 0xb0
	s_load_dwordx2 s[26:27], s[8:9], 0xb0
	s_nop 0
	s_load_dwordx2 s[28:29], s[28:29], 0xb0
	s_nop 0
	s_load_dwordx2 s[30:31], s[30:31], 0xa8
	s_nop 0
	s_load_dwordx2 s[8:9], s[34:35], 0xa8
	v_ashrrev_i16_sdwa v3, v10, sext(v3) dst_sel:DWORD dst_unused:UNUSED_PAD src0_sel:DWORD src1_sel:BYTE_0
	s_lshl_b32 s36, s25, 6
	s_lshl_b32 s4, s60, 8
	v_bfe_i32 v11, v3, 0, 16
	v_and_b32_e32 v3, 15, v2
	s_add_i32 s4, s4, s36
	v_or_b32_e32 v4, s4, v3
	v_ashrrev_i32_e32 v5, 31, v4
	v_lshl_add_u64 v[4:5], v[4:5], 2, s[10:11]
	global_load_dword v134, v[4:5], off
	global_load_dword v170, v[4:5], off offset:64
	global_load_dword v169, v[4:5], off offset:128
	global_load_dword v168, v[4:5], off offset:192
	global_load_dword v167, v[4:5], off offset:512
	global_load_dword v165, v[4:5], off offset:576
	global_load_dword v164, v[4:5], off offset:640
	global_load_dword v163, v[4:5], off offset:704
	v_and_b32_e32 v7, -16, v7
	v_add_u32_e32 v7, v8, v7
	v_lshlrev_b32_e32 v4, 1, v7
	v_lshrrev_b32_e32 v5, 2, v7
	v_and_b32_e32 v8, 3, v8
	s_mov_b32 s4, 0xfffe0
	v_and_b32_e32 v4, 24, v4
	v_and_b32_e32 v5, 4, v5
	v_and_or_b32 v8, v7, s4, v8
	v_or3_b32 v4, v8, v5, v4
	v_add_lshl_u32 v5, v9, v11, 1
	v_lshl_add_u32 v152, v4, 12, v5
	v_add_u32_e32 v4, 0x2000, v6
	v_lshl_add_u32 v151, v7, 12, v5
	v_ashrrev_i32_e32 v5, 31, v4
	v_lshrrev_b32_e32 v5, 22, v5
	v_add_u32_e32 v5, v4, v5
	v_ashrrev_i32_e32 v5, 10, v5
	v_mul_i32_i24_e32 v6, 0x400, v5
	v_sub_u32_e32 v4, v4, v6
	v_lshrrev_b32_e32 v6, 4, v4
	v_bitop3_b32 v4, v6, v4, 32 bitop3:0x6c
	v_ashrrev_i32_e32 v7, 31, v4
	v_lshrrev_b32_e32 v7, 26, v7
	v_lshlrev_b32_e32 v6, 3, v5
	v_add_u32_e32 v7, v4, v7
	v_and_b32_e32 v6, -16, v6
	v_ashrrev_i32_e32 v8, 6, v7
	v_add_u32_e32 v6, v8, v6
	v_and_b32_e32 v7, 0xc0, v7
	v_and_b32_e32 v8, 3, v8
	s_ashr_i32 s37, s2, 6
	v_sub_u32_e32 v4, v4, v7
	v_and_or_b32 v8, v6, s4, v8
	s_lshl_b32 s4, s37, 10
	s_ashr_i32 s23, s22, 31
	v_lshlrev_b32_e32 v5, 5, v5
	v_ashrrev_i16_sdwa v4, v10, sext(v4) dst_sel:DWORD dst_unused:UNUSED_PAD src0_sel:DWORD src1_sel:BYTE_0
	v_lshlrev_b32_e32 v7, 1, v6
	v_lshrrev_b32_e32 v9, 2, v6
	s_add_i32 s61, s4, 0
	s_lshl_b32 s12, s60, 20
	s_lshl_b64 s[4:5], s[22:23], 20
	v_and_b32_e32 v5, 32, v5
	v_bfe_i32 v4, v4, 0, 16
	v_and_b32_e32 v7, 24, v7
	v_and_b32_e32 v9, 4, v9
	s_add_u32 s6, s55, s4
	v_or3_b32 v7, v8, v9, v7
	v_add_lshl_u32 v4, v5, v4, 1
	s_addc_u32 s7, s57, s5
	s_add_i32 s23, s61, 0x10000
	s_mov_b32 m0, s23
	s_nop 0
	global_load_lds_dwordx4 v152, s[6:7]
	v_lshl_add_u32 v154, v7, 12, v4
	s_add_i32 s62, s61, 0x12000
	s_mov_b32 m0, s62
	s_nop 0
	global_load_lds_dwordx4 v154, s[6:7]
	s_add_u32 s4, s6, 0x80000
	s_addc_u32 s5, s7, 0
	s_add_i32 s63, s61, 0x14000
	s_mov_b32 m0, s63
	s_nop 0
	global_load_lds_dwordx4 v152, s[4:5]
	s_add_i32 s64, s61, 0x16000
	s_mov_b32 m0, s64
	s_nop 0
	global_load_lds_dwordx4 v154, s[4:5]
	s_add_u32 s4, s53, s12
	s_addc_u32 s5, s54, 0
	s_mov_b32 m0, s61
	s_nop 0
	global_load_lds_dwordx4 v151, s[4:5]
	s_add_i32 s65, s61, 0x2000
	v_lshl_add_u32 v153, v6, 12, v4
	s_mov_b32 m0, s65
	s_nop 0
	global_load_lds_dwordx4 v153, s[4:5]
	s_add_u32 s34, s4, 0x80000
	s_addc_u32 s35, s5, 0
	s_add_i32 s66, s61, 0x4000
	s_mov_b32 m0, s66
	s_nop 0
	global_load_lds_dwordx4 v151, s[34:35]
	s_add_i32 s67, s61, 0x6000
	s_mov_b32 m0, s67
	s_nop 0
	global_load_lds_dwordx4 v153, s[34:35]
	s_cmp_eq_u32 s25, 1
	s_mov_b32 s24, 0
	s_cselect_b64 s[12:13], -1, 0
	s_cmp_lg_u32 s25, 1
	s_cbranch_scc1 .LBB0_102
	s_barrier

;     __device__ bool next(int i, Unit& u) const {
;         const long L = (long)i * G + c; if (L >= nwg) return false;
;         int wgid = (int)L; { const int q = nwg / NXCD, r = nwg % NXCD, xcd = wgid % NXCD, off = wgid / NXCD; wgid = (xcd < r ? xcd * (q + 1) : r * (q + 1) + (xcd - r) * q) + off; }
;         const int nig = WGM * nN, gid = wgid / nig, fm = gid * WGM, gsz = (nM - fm) < WGM ? (nM - fm) : WGM;
;         u.pm = fm + ((wgid % nig) % gsz); u.pn = (wgid % nig) / gsz; return true;
.LBB0_1120:
	s_or_b64 exec, exec, s[4:5]
	s_mov_b64 s[10:11], s[0:1]
	s_mov_b64 s[12:13], s[0:1]
	s_mov_b64 s[4:5], s[0:1]
	s_mov_b64 s[2:3], s[0:1]
	s_waitcnt lgkmcnt(0)
	s_barrier
	v_readlane_b32 s99, v243, 40
	s_nop 1
	s_bitcmp1_b32 s99, 3
	s_cbranch_scc0 .Lstg_1
	s_sleep 18
.Lstg_1:
	v_cndmask_b32_e64 v3, 0, 1, s[14:15]
	v_cmp_ne_u32_e64 s[2:3], 1, v3
	s_mov_b64 s[16:17], s[0:1]
	v_mov_b32_e32 v2, v0
	v_writelane_b32 v242, s2, 18
	s_andn2_b64 vcc, exec, s[14:15]
	s_nop 0
	v_writelane_b32 v242, s3, 19
	v_readfirstlane_b32 s3, v2
	s_cbranch_vccnz .LBB0_1146
	s_load_dwordx2 s[14:15], s[10:11], 0xb0
	s_load_dwordx2 s[8:9], s[12:13], 0xb0
	s_lshr_b32 s2, s95, 29
	s_add_i32 s6, s94, s2
	s_and_b32 s2, s6, -8
	s_sub_i32 s7, s94, s2
	s_cmp_gt_i32 s7, -1
	s_cbranch_scc0 .LBB0_1123
	s_lshl_b32 s2, s7, 5
	s_load_dwordx2 s[10:11], s[4:5], 0xb0
	s_load_dwordx2 s[12:13], s[16:17], 0xb0
	s_cbranch_execz .LBB0_1124
	s_branch .LBB0_1125

; #define PG8_STAGE(bufoff, gbase, voff) do { _Pragma("unroll") for (int _i = 0; _i < 2; ++_i) { unsigned keep_; \
;         asm volatile("s_mov_b32 %0, m0\n\ts_mov_b32 m0, %3\n\ts_nop 0\n\tglobal_load_lds_dwordx4 %1, %2\n\ts_mov_b32 m0, %0" \
;             : "=&s"(keep_) : "v"((voff)[_i]), "s"((const void*)(gbase)), "s"(ldsb0 + (unsigned)(bufoff) + (unsigned)(_i * 8192)) : "memory"); } } while (0)
; #define PG8_WAIT_V(n) asm volatile("s_waitcnt vmcnt(" #n ")" ::: "memory")
; #define PG8_BAR __builtin_amdgcn_s_barrier()
;     __device__ bool next(int i, Unit& u) const {
;         const long L = (long)i * G + c; if (L >= nwg) return false;
;         int wgid = (int)L; { const int q = nwg / NXCD, r = nwg % NXCD, xcd = wgid % NXCD, off = wgid / NXCD; wgid = (xcd < r ? xcd * (q + 1) : r * (q + 1) + (xcd - r) * q) + off; }
;         const int nig = WGM * nN, gid = wgid / nig, fm = gid * WGM, gsz = (nM - fm) < WGM ? (nM - fm) : WGM;
;         u.pm = fm + ((wgid % nig) % gsz); u.pn = (wgid % nig) / gsz; return true;
; template <class Epi, class Sched, bool ALIGN_EPI>
; __device__ __forceinline__ void gemm_phase(LAS unsigned char* lds, const Gemm g, const Sched& S, const Epi& E) {
;     ...
;     Unit cur, nxt; int ui = 0;
;     if (!S.next(0, cur)) return;
;     f32x4 acc[2][2][4][2];
; #pragma unroll
;     for (int a = 0; a < 2; ++a)
; #pragma unroll
;         for (int b = 0; b < 2; ++b)
; #pragma unroll
;             for (int m = 0; m < 4; ++m)
; #pragma unroll
;                 for (int n = 0; n < 2; ++n) acc[a][b][m][n] = (f32x4){0.f, 0.f, 0.f, 0.f};
;     bf16x8 At[4][2], B0[2][2], B1[2][2];
;     float pre[Epi::NPRE > 0 ? Epi::NPRE : 1];
;     if constexpr (Epi::NPRE > 0) E.preload(cur, wr, fr, pre);
;     const char* cA = (const char*)g.A + (size_t)cur.pm * tstepA + (size_t)cur.pn * g.a_koff * 2; const char* cB = (const char*)g.Bt + (size_t)cur.pn * tstepB;
;     PG8_STAGE(PG8_SB(0, 0), cB, voffB); PG8_STAGE(PG8_SB(0, 1), cB + hstepB, voffB); PG8_STAGE(PG8_SA(0, 0), cA, voffA); PG8_STAGE(PG8_SA(0, 1), cA + hstepA, voffA);
;     if (wr == 1) PG8_BAR;
;     PG8_WAIT_V(2); PG8_BAR;
;     PG8_STAGE(PG8_SB(1, 0), cB + kstep, voffB); PG8_STAGE(PG8_SA(1, 0), cA + kstep, voffA); PG8_STAGE(PG8_SB(1, 1), cB + hstepB + kstep, voffB);
;     PG8_WAIT_V(6); PG8_BAR;
.LBB0_1205:
	s_or_b64 exec, exec, s[4:5]
	s_cmpk_lt_i32 s94, 0x5ac
	s_cselect_b64 s[6:7], -1, 0
	s_mov_b64 s[4:5], s[0:1]
	s_mov_b64 s[8:9], s[0:1]
	s_mov_b64 s[12:13], s[0:1]
	s_mov_b64 s[14:15], s[0:1]
	s_waitcnt lgkmcnt(0)
	v_mov_b32_e32 v2, v0
	s_barrier
	v_readlane_b32 s99, v243, 40
	s_nop 1
	s_bitcmp1_b32 s99, 3
	s_cbranch_scc0 .Lstg_2
	s_sleep 18
.Lstg_2:
	v_writelane_b32 v242, s6, 20
	v_readfirstlane_b32 s3, v2
	s_and_b64 vcc, exec, s[6:7]
	v_writelane_b32 v242, s7, 21
	s_cbranch_vccz .LBB0_1225
	s_load_dwordx2 s[6:7], s[4:5], 0xb0
	s_load_dwordx2 s[16:17], s[8:9], 0xb0
	s_load_dwordx2 s[18:19], s[12:13], 0xb0
	s_load_dwordx2 s[10:11], s[14:15], 0xb0
	v_bfe_i32 v4, v2, 27, 1
	s_waitcnt lgkmcnt(0)
	s_add_u32 s23, s6, 0x1d800000
	s_addc_u32 s24, s7, 0
	s_add_u32 s25, s16, 0x1b00000
	s_addc_u32 s44, s17, 0
	s_add_u32 s8, s18, 0x18400
	s_addc_u32 s9, s19, 0
	s_ashr_i32 s7, s3, 6
	s_lshl_b32 s2, s7, 10
	s_add_i32 s45, s2, 0
	s_lshr_b32 s2, s95, 29
	s_add_i32 s2, s94, s2
	s_and_b32 s4, s2, -8
	s_sub_i32 s4, s94, s4
	s_ashr_i32 s6, s3, 8
	s_mul_i32 s12, s4, 0xb5
	v_lshlrev_b32_e32 v8, 4, v2
	v_lshrrev_b32_e32 v4, 22, v4
	s_lshl_b32 s16, s6, 6
	s_add_i32 s12, s12, 4
	s_ashr_i32 s2, s2, 3
	v_add_u32_e32 v4, v8, v4
	s_mul_i32 s5, s4, 0xb6
	s_cmp_lt_i32 s4, 4
	v_and_b32_e32 v4, 0xfffffc00, v4
	s_cselect_b32 s4, s5, s12
	v_sub_u32_e32 v4, v8, v4
	s_add_i32 s4, s4, s2
	v_ashrrev_i32_e32 v3, 31, v2
	v_lshrrev_b32_e32 v5, 4, v4
	s_mul_hi_i32 s2, s4, 0x2e8ba2e9
	v_lshrrev_b32_e32 v3, 26, v3
	v_bitop3_b32 v5, v5, v4, 32 bitop3:0x6c
	v_ashrrev_i32_e32 v4, 31, v4
	s_lshr_b32 s5, s2, 31
	s_ashr_i32 s2, s2, 6
	v_add_u32_e32 v3, v2, v3
	v_lshrrev_b32_e32 v4, 26, v4
	s_add_i32 s2, s2, s5
	v_ashrrev_i32_e32 v3, 6, v3
	v_add_u32_e32 v4, v5, v4
	s_lshl_b32 s12, s2, 3
	v_lshlrev_b32_e32 v6, 3, v3
	v_ashrrev_i32_e32 v9, 6, v4
	v_lshlrev_b32_e32 v3, 5, v3
	s_sub_i32 s5, 33, s12
	s_mulk_i32 s2, 0x160
	v_and_b32_e32 v11, 32, v3
	v_mul_i32_i24_e32 v3, 64, v9
	s_min_u32 s13, s5, 8
	s_sub_i32 s2, s4, s2
	v_and_b32_e32 v6, -16, v6
	v_sub_u32_e32 v12, v5, v3
	s_sext_i32_i16 s4, s2
	v_cvt_f32_ubyte0_e32 v5, s13
	v_add_u32_e32 v10, v9, v6
	v_cvt_f32_i32_e32 v4, s4
	v_rcp_iflag_f32_e32 v6, v5
	s_ashr_i32 s4, s4, 30
	s_or_b32 s14, s4, 1
	v_and_b32_e32 v3, 15, v2
	v_mul_f32_e32 v6, v4, v6
	v_trunc_f32_e32 v6, v6
	v_fma_f32 v4, -v6, v5, v4
	v_cvt_i32_f32_e32 v6, v6
	v_cmp_ge_f32_e64 s[4:5], |v4|, v5
	s_and_b64 s[4:5], s[4:5], exec
	s_cselect_b32 s4, s14, 0
	v_readfirstlane_b32 s5, v6
	s_add_i32 s14, s5, s4
	s_mul_i32 s4, s14, s13
	s_sub_i32 s2, s2, s4
	s_sext_i32_i16 s2, s2
	s_add_i32 s4, s12, s2
	s_lshl_b32 s2, s4, 8
	s_add_i32 s2, s2, s16
	v_or_b32_e32 v4, s2, v3
	v_ashrrev_i32_e32 v5, 31, v4
	v_lshl_add_u64 v[6:7], v[4:5], 2, s[8:9]
	v_add_u32_e32 v4, 0x80, v4
	v_ashrrev_i32_e32 v5, 31, v4
	v_lshl_add_u64 v[4:5], v[4:5], 2, s[8:9]
	global_load_dword v153, v[6:7], off
	global_load_dword v152, v[6:7], off offset:64
	global_load_dword v151, v[6:7], off offset:128
	global_load_dword v150, v[6:7], off offset:192
	global_load_dword v149, v[4:5], off
	global_load_dword v148, v[4:5], off offset:64
	global_load_dword v147, v[4:5], off offset:128
	global_load_dword v139, v[4:5], off offset:192
	v_mov_b32_e32 v13, 1
	v_ashrrev_i16_sdwa v4, v13, sext(v12) dst_sel:DWORD dst_unused:UNUSED_PAD src0_sel:DWORD src1_sel:BYTE_0
	v_lshlrev_b32_e32 v5, 1, v10
	v_lshrrev_b32_e32 v6, 2, v10
	v_and_b32_e32 v7, 3, v9
	s_mov_b32 s2, 0xfffe0
	v_bfe_i32 v4, v4, 0, 16
	v_and_b32_e32 v5, 24, v5
	v_and_b32_e32 v6, 4, v6
	v_and_or_b32 v7, v10, s2, v7
	v_or3_b32 v5, v7, v6, v5
	v_add_lshl_u32 v4, v11, v4, 1
	s_waitcnt vmcnt(11)
	v_lshl_add_u32 v134, v10, 12, v4
	s_waitcnt vmcnt(8)
	v_lshl_add_u32 v135, v5, 12, v4
	v_add_u32_e32 v4, 0x2000, v8
	v_ashrrev_i32_e32 v5, 31, v4
	v_lshrrev_b32_e32 v5, 22, v5
	v_add_u32_e32 v5, v4, v5
	v_ashrrev_i32_e32 v5, 10, v5
	v_mul_i32_i24_e32 v6, 0x400, v5
	v_sub_u32_e32 v4, v4, v6
	v_lshrrev_b32_e32 v6, 4, v4
	v_bitop3_b32 v4, v6, v4, 32 bitop3:0x6c
	v_ashrrev_i32_e32 v7, 31, v4
	v_lshrrev_b32_e32 v7, 26, v7
	v_lshlrev_b32_e32 v6, 3, v5
	v_add_u32_e32 v7, v4, v7
	v_and_b32_e32 v6, -16, v6
	v_ashrrev_i32_e32 v8, 6, v7
	v_and_b32_e32 v7, 0xc0, v7
	v_add_u32_e32 v6, v8, v6
	v_sub_u32_e32 v4, v4, v7
	s_ashr_i32 s5, s4, 31
	s_bfe_i64 s[18:19], s[14:15], 0x100000
	v_lshlrev_b32_e32 v5, 5, v5
	v_ashrrev_i16_sdwa v4, v13, sext(v4) dst_sel:DWORD dst_unused:UNUSED_PAD src0_sel:DWORD src1_sel:BYTE_0
	v_lshlrev_b32_e32 v7, 1, v6
	v_lshrrev_b32_e32 v9, 2, v6
	v_and_b32_e32 v8, 3, v8
	s_lshl_b64 s[12:13], s[4:5], 20
	s_lshl_b64 s[18:19], s[18:19], 20
	v_and_b32_e32 v5, 32, v5
	v_bfe_i32 v4, v4, 0, 16
	v_and_b32_e32 v7, 24, v7
	v_and_b32_e32 v9, 4, v9
	v_and_or_b32 v8, v6, s2, v8
	s_add_u32 s36, s25, s18
	v_or3_b32 v7, v8, v9, v7
	v_add_lshl_u32 v4, v5, v4, 1
	s_addc_u32 s37, s44, s19
	s_add_i32 s47, s45, 0x10000
	s_mov_b32 m0, s47
	s_nop 0
	global_load_lds_dwordx4 v135, s[36:37]
	s_add_i32 s48, s45, 0x12000
	v_lshl_add_u32 v137, v7, 12, v4
	s_mov_b32 m0, s48
	s_nop 0
	global_load_lds_dwordx4 v137, s[36:37]
	s_add_u32 s18, s36, 0x80000
	s_addc_u32 s19, s37, 0
	s_add_i32 s49, s45, 0x14000
	s_mov_b32 m0, s49
	s_nop 0
	global_load_lds_dwordx4 v135, s[18:19]
	s_add_i32 s50, s45, 0x16000
	s_mov_b32 m0, s50
	s_nop 0
	global_load_lds_dwordx4 v137, s[18:19]
	s_add_u32 s34, s23, s12
	s_addc_u32 s35, s24, s13
	s_mov_b32 m0, s45
	s_nop 0
	global_load_lds_dwordx4 v134, s[34:35]
	s_add_i32 s51, s45, 0x2000
	v_lshl_add_u32 v136, v6, 12, v4
	s_mov_b32 m0, s51
	s_nop 0
	global_load_lds_dwordx4 v136, s[34:35]
	s_add_u32 s18, s34, 0x80000
	s_addc_u32 s19, s35, 0
	s_add_i32 s52, s45, 0x4000
	s_mov_b32 m0, s52
	s_nop 0
	global_load_lds_dwordx4 v134, s[18:19]
	s_add_i32 s53, s45, 0x6000
	s_mov_b32 m0, s53
	s_nop 0
	global_load_lds_dwordx4 v136, s[18:19]
	s_cmp_eq_u32 s6, 1
	s_mov_b32 s46, 0
	s_cselect_b64 s[12:13], -1, 0
	s_cmp_lg_u32 s6, 1
	s_cbranch_scc1 .LBB0_1208
	s_barrier

;     __device__ bool next(int i, Unit& u) const {
;         const long L = (long)i * G + c; if (L >= nwg) return false;
;         int wgid = (int)L; { const int q = nwg / NXCD, r = nwg % NXCD, xcd = wgid % NXCD, off = wgid / NXCD; wgid = (xcd < r ? xcd * (q + 1) : r * (q + 1) + (xcd - r) * q) + off; }
;         const int nig = WGM * nN, gid = wgid / nig, fm = gid * WGM, gsz = (nM - fm) < WGM ? (nM - fm) : WGM;
;         u.pm = fm + ((wgid % nig) % gsz); u.pn = (wgid % nig) / gsz; return true;
.Lstg_3:
	s_mov_b64 s[16:17], s[0:1]
	v_readlane_b32 s2, v242, 18
	v_mov_b32_e32 v2, v0
	v_readlane_b32 s3, v242, 19
	s_and_b64 vcc, exec, s[2:3]
	v_readfirstlane_b32 s6, v2
	s_cbranch_vccnz .LBB0_1326
	s_load_dwordx2 s[14:15], s[10:11], 0xb0
	s_load_dwordx2 s[8:9], s[12:13], 0xb0
	s_lshr_b32 s2, s95, 29
	s_add_i32 s3, s94, s2
	s_and_b32 s2, s3, -8
	s_sub_i32 s7, s94, s2
	s_cmp_gt_i32 s7, -1
	s_cbranch_scc0 .LBB0_1299
	s_lshl_b32 s2, s7, 5
	s_load_dwordx2 s[10:11], s[4:5], 0xb0
	s_load_dwordx2 s[12:13], s[16:17], 0xb0
	s_cbranch_execz .LBB0_1300
	s_branch .LBB0_1301

; #define PG8_STAGE(bufoff, gbase, voff) do { _Pragma("unroll") for (int _i = 0; _i < 2; ++_i) { unsigned keep_; \
;         asm volatile("s_mov_b32 %0, m0\n\ts_mov_b32 m0, %3\n\ts_nop 0\n\tglobal_load_lds_dwordx4 %1, %2\n\ts_mov_b32 m0, %0" \
;             : "=&s"(keep_) : "v"((voff)[_i]), "s"((const void*)(gbase)), "s"(ldsb0 + (unsigned)(bufoff) + (unsigned)(_i * 8192)) : "memory"); } } while (0)
; #define PG8_WAIT_V(n) asm volatile("s_waitcnt vmcnt(" #n ")" ::: "memory")
; #define PG8_BAR __builtin_amdgcn_s_barrier()
; template <class Epi, class Sched, bool ALIGN_EPI>
; __device__ __forceinline__ void gemm_phase(LAS unsigned char* lds, const Gemm g, const Sched& S, const Epi& E) {
;     ...
;     Unit cur, nxt; int ui = 0;
;     if (!S.next(0, cur)) return;
;     f32x4 acc[2][2][4][2];
; #pragma unroll
;     for (int a = 0; a < 2; ++a)
; #pragma unroll
;         for (int b = 0; b < 2; ++b)
; #pragma unroll
;             for (int m = 0; m < 4; ++m)
; #pragma unroll
;                 for (int n = 0; n < 2; ++n) acc[a][b][m][n] = (f32x4){0.f, 0.f, 0.f, 0.f};
;     bf16x8 At[4][2], B0[2][2], B1[2][2];
;     float pre[Epi::NPRE > 0 ? Epi::NPRE : 1];
;     if constexpr (Epi::NPRE > 0) E.preload(cur, wr, fr, pre);
;     const char* cA = (const char*)g.A + (size_t)cur.pm * tstepA + (size_t)cur.pn * g.a_koff * 2; const char* cB = (const char*)g.Bt + (size_t)cur.pn * tstepB;
;     PG8_STAGE(PG8_SB(0, 0), cB, voffB); PG8_STAGE(PG8_SB(0, 1), cB + hstepB, voffB); PG8_STAGE(PG8_SA(0, 0), cA, voffA); PG8_STAGE(PG8_SA(0, 1), cA + hstepA, voffA);
;     if (wr == 1) PG8_BAR;
;     PG8_WAIT_V(2); PG8_BAR;
;     PG8_STAGE(PG8_SB(1, 0), cB + kstep, voffB); PG8_STAGE(PG8_SA(1, 0), cA + kstep, voffA); PG8_STAGE(PG8_SB(1, 1), cB + hstepB + kstep, voffB);
;     PG8_WAIT_V(6); PG8_BAR;
; __global__ void __launch_bounds__(NT, 2) fwd(Args args) {
;     ...
;         pg8::Gemm g{HB, WQKV, DM, DM, DM, 0}; EpiQkv E{ssq + 2 * MPAD, QB, KB, VB, out + O_SKP, out + O_SVP};
;         pg8::BalancedOrder S{3, bx, G}; pg8::gemm_phase<EpiQkv, pg8::BalancedOrder, true>(lds, g, S, E);
.LBB0_1395:
	s_or_b64 exec, exec, s[4:5]
	s_cmpk_lt_i32 s94, 0x300
	v_readlane_b32 s18, v242, 10
	s_cselect_b64 s[6:7], -1, 0
	v_readlane_b32 s19, v242, 11
	s_mov_b64 s[12:13], s[0:1]
	s_mov_b64 s[14:15], s[0:1]
	s_mov_b64 s[16:17], s[0:1]
	s_mov_b64 s[8:9], s[0:1]
	s_mov_b64 s[26:27], s[0:1]
	s_mov_b64 s[4:5], s[0:1]
	s_mov_b64 s[10:11], s[0:1]
	s_mov_b64 s[30:31], s[0:1]
	s_waitcnt lgkmcnt(0)
	v_mov_b32_e32 v2, v0
	s_or_b64 s[6:7], s[18:19], s[6:7]
	s_barrier
	v_readlane_b32 s99, v243, 40
	s_nop 1
	s_bitcmp1_b32 s99, 3
	s_cbranch_scc0 .Lstg_4
	s_sleep 18
.Lstg_4:
	s_and_b64 vcc, exec, s[6:7]
	v_readfirstlane_b32 s2, v2
	s_cbranch_vccz .LBB0_1544
	v_bfe_i32 v4, v2, 27, 1
	v_lshlrev_b32_e32 v6, 4, v2
	v_lshrrev_b32_e32 v4, 22, v4
	v_add_u32_e32 v4, v6, v4
	v_and_b32_e32 v4, 0xfffffc00, v4
	v_sub_u32_e32 v4, v6, v4
	s_load_dwordx2 s[6:7], s[12:13], 0xb0
	s_nop 0
	s_load_dwordx2 s[14:15], s[14:15], 0xb0
	s_nop 0
	s_load_dwordx2 s[16:17], s[16:17], 0xb0
	s_nop 0
	s_load_dwordx2 s[18:19], s[8:9], 0xb0
	s_load_dwordx2 s[12:13], s[26:27], 0xb0
	v_ashrrev_i32_e32 v3, 31, v2
	v_lshrrev_b32_e32 v5, 4, v4
	s_waitcnt lgkmcnt(0)
	s_add_u32 s48, s6, 0x1d800000
	v_lshrrev_b32_e32 v3, 26, v3
	v_bitop3_b32 v5, v5, v4, 32 bitop3:0x6c
	v_ashrrev_i32_e32 v4, 31, v4
	s_addc_u32 s49, s7, 0
	v_add_u32_e32 v3, v2, v3
	v_lshrrev_b32_e32 v4, 26, v4
	s_add_u32 s50, s14, 0x5d00000
	v_ashrrev_i32_e32 v3, 6, v3
	v_add_u32_e32 v4, v5, v4
	s_addc_u32 s51, s15, 0
	v_lshlrev_b32_e32 v7, 3, v3
	v_ashrrev_i32_e32 v8, 6, v4
	v_lshlrev_b32_e32 v3, 5, v3
	s_add_u32 s14, s16, 0x20800
	v_and_b32_e32 v9, 32, v3
	v_mul_i32_i24_e32 v3, 64, v8
	s_addc_u32 s15, s17, 0
	s_ashr_i32 s6, s2, 8
	v_sub_u32_e32 v3, v5, v3
	v_mov_b32_e32 v10, 1
	v_ashrrev_i16_sdwa v3, v10, sext(v3) dst_sel:DWORD dst_unused:UNUSED_PAD src0_sel:DWORD src1_sel:BYTE_0
	s_lshl_b32 s7, s6, 6
	s_lshl_b32 s3, s60, 8
	v_bfe_i32 v11, v3, 0, 16
	v_and_b32_e32 v3, 15, v2
	s_add_i32 s3, s3, s7
	v_or_b32_e32 v4, s3, v3
	v_ashrrev_i32_e32 v5, 31, v4
	v_lshl_add_u64 v[4:5], v[4:5], 2, s[14:15]
	s_load_dwordx2 s[26:27], s[4:5], 0xb0
	s_load_dwordx2 s[28:29], s[10:11], 0xa8
	s_nop 0
	s_load_dwordx2 s[10:11], s[30:31], 0xa8
	global_load_dword v130, v[4:5], off
	global_load_dword v159, v[4:5], off offset:64
	global_load_dword v158, v[4:5], off offset:128
	global_load_dword v156, v[4:5], off offset:192
	global_load_dword v155, v[4:5], off offset:512
	global_load_dword v154, v[4:5], off offset:576
	global_load_dword v153, v[4:5], off offset:640
	global_load_dword v152, v[4:5], off offset:704
	v_and_b32_e32 v7, -16, v7
	v_add_u32_e32 v7, v8, v7
	v_lshlrev_b32_e32 v4, 1, v7
	v_lshrrev_b32_e32 v5, 2, v7
	v_and_b32_e32 v8, 3, v8
	s_mov_b32 s3, 0xfffe0
	v_and_b32_e32 v4, 24, v4
	v_and_b32_e32 v5, 4, v5
	v_and_or_b32 v8, v7, s3, v8
	v_or3_b32 v4, v8, v5, v4
	v_add_lshl_u32 v5, v9, v11, 1
	s_waitcnt vmcnt(9)
	v_lshl_add_u32 v141, v4, 12, v5
	v_add_u32_e32 v4, 0x2000, v6
	v_lshl_add_u32 v140, v7, 12, v5
	v_ashrrev_i32_e32 v5, 31, v4
	v_lshrrev_b32_e32 v5, 22, v5
	v_add_u32_e32 v5, v4, v5
	v_ashrrev_i32_e32 v5, 10, v5
	v_mul_i32_i24_e32 v6, 0x400, v5
	v_sub_u32_e32 v4, v4, v6
	v_lshrrev_b32_e32 v6, 4, v4
	v_bitop3_b32 v4, v6, v4, 32 bitop3:0x6c
	v_ashrrev_i32_e32 v7, 31, v4
	v_lshrrev_b32_e32 v7, 26, v7
	v_lshlrev_b32_e32 v6, 3, v5
	v_add_u32_e32 v7, v4, v7
	v_and_b32_e32 v6, -16, v6
	v_ashrrev_i32_e32 v8, 6, v7
	v_and_b32_e32 v7, 0xc0, v7
	s_ashr_i32 s34, s2, 6
	v_add_u32_e32 v6, v8, v6
	v_sub_u32_e32 v4, v4, v7
	s_lshl_b32 s4, s34, 10
	s_ashr_i32 s23, s22, 31
	v_lshlrev_b32_e32 v5, 5, v5
	v_ashrrev_i16_sdwa v4, v10, sext(v4) dst_sel:DWORD dst_unused:UNUSED_PAD src0_sel:DWORD src1_sel:BYTE_0
	v_lshlrev_b32_e32 v7, 1, v6
	v_lshrrev_b32_e32 v9, 2, v6
	v_and_b32_e32 v8, 3, v8
	s_add_i32 s52, s4, 0
	s_lshl_b32 s16, s60, 20
	s_lshl_b64 s[4:5], s[22:23], 20
	v_and_b32_e32 v5, 32, v5
	v_bfe_i32 v4, v4, 0, 16
	v_and_b32_e32 v7, 24, v7
	v_and_b32_e32 v9, 4, v9
	v_and_or_b32 v8, v6, s3, v8
	s_add_u32 s8, s50, s4
	v_or3_b32 v7, v8, v9, v7
	v_add_lshl_u32 v4, v5, v4, 1
	s_addc_u32 s9, s51, s5
	s_add_i32 s53, s52, 0x10000
	s_mov_b32 m0, s53
	s_nop 0
	global_load_lds_dwordx4 v141, s[8:9]
	v_lshl_add_u32 v143, v7, 12, v4
	s_add_i32 s54, s52, 0x12000
	s_mov_b32 m0, s54
	s_nop 0
	global_load_lds_dwordx4 v143, s[8:9]
	s_add_u32 s4, s8, 0x80000
	s_addc_u32 s5, s9, 0
	s_add_i32 s55, s52, 0x14000
	s_mov_b32 m0, s55
	s_nop 0
	global_load_lds_dwordx4 v141, s[4:5]
	s_add_i32 s56, s52, 0x16000
	s_mov_b32 m0, s56
	s_nop 0
	global_load_lds_dwordx4 v143, s[4:5]
	s_add_u32 s4, s48, s16
	s_addc_u32 s5, s49, 0
	s_mov_b32 m0, s52
	s_nop 0
	global_load_lds_dwordx4 v140, s[4:5]
	s_add_i32 s57, s52, 0x2000
	v_lshl_add_u32 v142, v6, 12, v4
	s_mov_b32 m0, s57
	s_nop 0
	global_load_lds_dwordx4 v142, s[4:5]
	s_add_u32 s24, s4, 0x80000
	s_addc_u32 s25, s5, 0
	s_add_i32 s59, s52, 0x4000
	s_mov_b32 m0, s59
	s_nop 0
	global_load_lds_dwordx4 v140, s[24:25]
	s_add_i32 s61, s52, 0x6000
	s_mov_b32 m0, s61
	s_nop 0
	global_load_lds_dwordx4 v142, s[24:25]
	s_cmp_eq_u32 s6, 1
	s_mov_b32 s3, 0
	s_cselect_b64 s[16:17], -1, 0
	s_cmp_lg_u32 s6, 1
	s_cbranch_scc1 .LBB0_1398
	s_barrier

;     __device__ bool next(int i, Unit& u) const {
;         const long L = (long)i * G + c; if (L >= nwg) return false;
;         int wgid = (int)L; { const int q = nwg / NXCD, r = nwg % NXCD, xcd = wgid % NXCD, off = wgid / NXCD; wgid = (xcd < r ? xcd * (q + 1) : r * (q + 1) + (xcd - r) * q) + off; }
;         const int nig = WGM * nN, gid = wgid / nig, fm = gid * WGM, gsz = (nM - fm) < WGM ? (nM - fm) : WGM;
;         u.pm = fm + ((wgid % nig) % gsz); u.pn = (wgid % nig) / gsz; return true;
.LBB0_1977:
	s_or_b64 exec, exec, s[4:5]
	s_mov_b64 s[10:11], s[0:1]
	s_mov_b64 s[12:13], s[0:1]
	s_mov_b64 s[8:9], s[0:1]
	s_mov_b64 s[2:3], s[0:1]
	s_waitcnt lgkmcnt(0)
	s_barrier
	v_readlane_b32 s99, v243, 40
	s_nop 1
	s_bitcmp1_b32 s99, 3
	s_cbranch_scc0 .Lstg_5
	s_sleep 18
.Lstg_5:
	s_mov_b64 s[16:17], s[0:1]
	v_readlane_b32 s2, v242, 18
	v_mov_b32_e32 v2, v0
	v_readlane_b32 s3, v242, 19
	s_and_b64 vcc, exec, s[2:3]
	v_readfirstlane_b32 s3, v2
	s_cbranch_vccnz .LBB0_2003
	s_load_dwordx2 s[14:15], s[10:11], 0xb0
	s_load_dwordx2 s[4:5], s[12:13], 0xb0
	s_lshr_b32 s2, s93, 29
	s_add_i32 s6, s92, s2
	s_and_b32 s2, s6, -8
	s_sub_i32 s7, s92, s2
	s_cmp_gt_i32 s7, -1
	s_cbranch_scc0 .LBB0_1980
	s_lshl_b32 s2, s7, 5
	s_load_dwordx2 s[10:11], s[8:9], 0xb0
	s_load_dwordx2 s[12:13], s[16:17], 0xb0
	s_cbranch_execz .LBB0_1981
	s_branch .LBB0_1982

; #define PG8_STAGE(bufoff, gbase, voff) do { _Pragma("unroll") for (int _i = 0; _i < 2; ++_i) { unsigned keep_; \
;         asm volatile("s_mov_b32 %0, m0\n\ts_mov_b32 m0, %3\n\ts_nop 0\n\tglobal_load_lds_dwordx4 %1, %2\n\ts_mov_b32 m0, %0" \
;             : "=&s"(keep_) : "v"((voff)[_i]), "s"((const void*)(gbase)), "s"(ldsb0 + (unsigned)(bufoff) + (unsigned)(_i * 8192)) : "memory"); } } while (0)
; #define PG8_WAIT_V(n) asm volatile("s_waitcnt vmcnt(" #n ")" ::: "memory")
; #define PG8_BAR __builtin_amdgcn_s_barrier()
;     __device__ bool next(int i, Unit& u) const {
;         const long L = (long)i * G + c; if (L >= nwg) return false;
;         int wgid = (int)L; { const int q = nwg / NXCD, r = nwg % NXCD, xcd = wgid % NXCD, off = wgid / NXCD; wgid = (xcd < r ? xcd * (q + 1) : r * (q + 1) + (xcd - r) * q) + off; }
;         const int nig = WGM * nN, gid = wgid / nig, fm = gid * WGM, gsz = (nM - fm) < WGM ? (nM - fm) : WGM;
;         u.pm = fm + ((wgid % nig) % gsz); u.pn = (wgid % nig) / gsz; return true;
; template <class Epi, class Sched, bool ALIGN_EPI>
; __device__ __forceinline__ void gemm_phase(LAS unsigned char* lds, const Gemm g, const Sched& S, const Epi& E) {
;     ...
;     Unit cur, nxt; int ui = 0;
;     if (!S.next(0, cur)) return;
;     f32x4 acc[2][2][4][2];
; #pragma unroll
;     for (int a = 0; a < 2; ++a)
; #pragma unroll
;         for (int b = 0; b < 2; ++b)
; #pragma unroll
;             for (int m = 0; m < 4; ++m)
; #pragma unroll
;                 for (int n = 0; n < 2; ++n) acc[a][b][m][n] = (f32x4){0.f, 0.f, 0.f, 0.f};
;     bf16x8 At[4][2], B0[2][2], B1[2][2];
;     float pre[Epi::NPRE > 0 ? Epi::NPRE : 1];
;     if constexpr (Epi::NPRE > 0) E.preload(cur, wr, fr, pre);
;     const char* cA = (const char*)g.A + (size_t)cur.pm * tstepA + (size_t)cur.pn * g.a_koff * 2; const char* cB = (const char*)g.Bt + (size_t)cur.pn * tstepB;
;     PG8_STAGE(PG8_SB(0, 0), cB, voffB); PG8_STAGE(PG8_SB(0, 1), cB + hstepB, voffB); PG8_STAGE(PG8_SA(0, 0), cA, voffA); PG8_STAGE(PG8_SA(0, 1), cA + hstepA, voffA);
;     if (wr == 1) PG8_BAR;
;     PG8_WAIT_V(2); PG8_BAR;
;     PG8_STAGE(PG8_SB(1, 0), cB + kstep, voffB); PG8_STAGE(PG8_SA(1, 0), cA + kstep, voffA); PG8_STAGE(PG8_SB(1, 1), cB + hstepB + kstep, voffB);
;     PG8_WAIT_V(6); PG8_BAR;
.LBB0_2062:
	s_or_b64 exec, exec, s[4:5]
	v_readlane_b32 s6, v242, 20
	s_mov_b64 s[4:5], s[0:1]
	s_mov_b64 s[8:9], s[0:1]
	s_mov_b64 s[12:13], s[0:1]
	s_mov_b64 s[14:15], s[0:1]
	s_waitcnt lgkmcnt(0)
	v_mov_b32_e32 v2, v0
	v_readlane_b32 s7, v242, 21
	s_barrier
	v_readlane_b32 s99, v243, 40
	s_nop 1
	s_bitcmp1_b32 s99, 3
	s_cbranch_scc0 .Lstg_6
	s_sleep 18
.Lstg_6:
	s_and_b64 vcc, exec, s[6:7]
	v_readfirstlane_b32 s3, v2
	s_cbranch_vccz .LBB0_2082
	s_load_dwordx2 s[6:7], s[4:5], 0xb0
	s_load_dwordx2 s[16:17], s[8:9], 0xb0
	s_load_dwordx2 s[18:19], s[12:13], 0xb0
	s_load_dwordx2 s[10:11], s[14:15], 0xb0
	v_bfe_i32 v4, v2, 27, 1
	s_waitcnt lgkmcnt(0)
	s_add_u32 s38, s6, 0x1d800000
	s_addc_u32 s39, s7, 0
	s_add_u32 s40, s16, 0x7d00000
	s_addc_u32 s41, s17, 0
	s_add_u32 s8, s18, 0x28c00
	s_addc_u32 s9, s19, 0
	s_ashr_i32 s7, s3, 6
	s_lshl_b32 s2, s7, 10
	s_add_i32 s42, s2, 0
	s_lshr_b32 s2, s93, 29
	s_add_i32 s2, s92, s2
	s_ashr_i32 s4, s2, 3
	s_and_b32 s2, s2, -8
	s_sub_i32 s2, s92, s2
	s_ashr_i32 s6, s3, 8
	s_mul_i32 s12, s2, 0xb5
	v_lshlrev_b32_e32 v8, 4, v2
	v_lshrrev_b32_e32 v4, 22, v4
	s_lshl_b32 s16, s6, 6
	s_add_i32 s12, s12, 4
	v_add_u32_e32 v4, v8, v4
	s_mul_i32 s5, s2, 0xb6
	s_cmp_lt_i32 s2, 4
	v_and_b32_e32 v4, 0xfffffc00, v4
	s_cselect_b32 s2, s5, s12
	v_sub_u32_e32 v4, v8, v4
	s_add_i32 s2, s2, s4
	v_ashrrev_i32_e32 v3, 31, v2
	v_lshrrev_b32_e32 v5, 4, v4
	s_mul_hi_i32 s4, s2, 0x2e8ba2e9
	v_lshrrev_b32_e32 v3, 26, v3
	v_bitop3_b32 v5, v5, v4, 32 bitop3:0x6c
	v_ashrrev_i32_e32 v4, 31, v4
	s_lshr_b32 s5, s4, 31
	s_ashr_i32 s4, s4, 6
	v_add_u32_e32 v3, v2, v3
	v_lshrrev_b32_e32 v4, 26, v4
	s_add_i32 s4, s4, s5
	v_ashrrev_i32_e32 v3, 6, v3
	v_add_u32_e32 v4, v5, v4
	s_lshl_b32 s12, s4, 3
	v_lshlrev_b32_e32 v6, 3, v3
	v_ashrrev_i32_e32 v9, 6, v4
	v_lshlrev_b32_e32 v3, 5, v3
	s_sub_i32 s5, 33, s12
	v_and_b32_e32 v11, 32, v3
	v_mul_i32_i24_e32 v3, 64, v9
	s_min_u32 s13, s5, 8
	s_mulk_i32 s4, 0x160
	v_and_b32_e32 v6, -16, v6
	v_sub_u32_e32 v12, v5, v3
	s_sub_i32 s2, s2, s4
	v_cvt_f32_ubyte0_e32 v5, s13
	v_add_u32_e32 v10, v9, v6
	v_cvt_f32_i32_e32 v4, s2
	v_rcp_iflag_f32_e32 v6, v5
	s_ashr_i32 s4, s2, 30
	s_or_b32 s14, s4, 1
	v_and_b32_e32 v3, 15, v2
	v_mul_f32_e32 v6, v4, v6
	v_trunc_f32_e32 v6, v6
	v_fma_f32 v4, -v6, v5, v4
	v_cvt_i32_f32_e32 v6, v6
	v_cmp_ge_f32_e64 s[4:5], |v4|, v5
	s_and_b64 s[4:5], s[4:5], exec
	s_cselect_b32 s4, s14, 0
	v_readfirstlane_b32 s5, v6
	s_add_i32 s14, s5, s4
	s_mul_i32 s4, s14, s13
	s_sub_i32 s2, s2, s4
	s_sext_i32_i16 s2, s2
	s_add_i32 s4, s12, s2
	s_lshl_b32 s2, s4, 8
	s_add_i32 s2, s2, s16
	v_or_b32_e32 v4, s2, v3
	v_ashrrev_i32_e32 v5, 31, v4
	v_lshl_add_u64 v[6:7], v[4:5], 2, s[8:9]
	v_add_u32_e32 v4, 0x80, v4
	v_ashrrev_i32_e32 v5, 31, v4
	v_lshl_add_u64 v[4:5], v[4:5], 2, s[8:9]
	global_load_dword v153, v[6:7], off
	global_load_dword v152, v[6:7], off offset:64
	global_load_dword v151, v[6:7], off offset:128
	global_load_dword v150, v[6:7], off offset:192
	global_load_dword v149, v[4:5], off
	global_load_dword v148, v[4:5], off offset:64
	global_load_dword v147, v[4:5], off offset:128
	global_load_dword v139, v[4:5], off offset:192
	v_mov_b32_e32 v13, 1
	v_ashrrev_i16_sdwa v4, v13, sext(v12) dst_sel:DWORD dst_unused:UNUSED_PAD src0_sel:DWORD src1_sel:BYTE_0
	v_lshlrev_b32_e32 v5, 1, v10
	v_lshrrev_b32_e32 v6, 2, v10
	v_and_b32_e32 v7, 3, v9
	s_mov_b32 s2, 0xfffe0
	v_bfe_i32 v4, v4, 0, 16
	v_and_b32_e32 v5, 24, v5
	v_and_b32_e32 v6, 4, v6
	v_and_or_b32 v7, v10, s2, v7
	v_or3_b32 v5, v7, v6, v5
	v_add_lshl_u32 v4, v11, v4, 1
	s_waitcnt vmcnt(10)
	v_lshl_add_u32 v134, v10, 12, v4
	s_waitcnt vmcnt(8)
	v_lshl_add_u32 v135, v5, 12, v4
	v_add_u32_e32 v4, 0x2000, v8
	v_ashrrev_i32_e32 v5, 31, v4
	v_lshrrev_b32_e32 v5, 22, v5
	v_add_u32_e32 v5, v4, v5
	v_ashrrev_i32_e32 v5, 10, v5
	v_mul_i32_i24_e32 v6, 0x400, v5
	v_sub_u32_e32 v4, v4, v6
	v_lshrrev_b32_e32 v6, 4, v4
	v_bitop3_b32 v4, v6, v4, 32 bitop3:0x6c
	v_ashrrev_i32_e32 v7, 31, v4
	v_lshrrev_b32_e32 v7, 26, v7
	v_lshlrev_b32_e32 v6, 3, v5
	v_add_u32_e32 v7, v4, v7
	v_and_b32_e32 v6, -16, v6
	v_ashrrev_i32_e32 v8, 6, v7
	v_and_b32_e32 v7, 0xc0, v7
	v_add_u32_e32 v6, v8, v6
	v_sub_u32_e32 v4, v4, v7
	s_ashr_i32 s5, s4, 31
	s_bfe_i64 s[18:19], s[14:15], 0x100000
	v_lshlrev_b32_e32 v5, 5, v5
	v_ashrrev_i16_sdwa v4, v13, sext(v4) dst_sel:DWORD dst_unused:UNUSED_PAD src0_sel:DWORD src1_sel:BYTE_0
	v_lshlrev_b32_e32 v7, 1, v6
	v_lshrrev_b32_e32 v9, 2, v6
	v_and_b32_e32 v8, 3, v8
	s_lshl_b64 s[12:13], s[4:5], 20
	s_lshl_b64 s[18:19], s[18:19], 20
	v_and_b32_e32 v5, 32, v5
	v_bfe_i32 v4, v4, 0, 16
	v_and_b32_e32 v7, 24, v7
	v_and_b32_e32 v9, 4, v9
	v_and_or_b32 v8, v6, s2, v8
	s_add_u32 s28, s40, s18
	v_or3_b32 v7, v8, v9, v7
	v_add_lshl_u32 v4, v5, v4, 1
	s_addc_u32 s29, s41, s19
	s_add_i32 s44, s42, 0x10000
	s_mov_b32 m0, s44
	s_nop 0
	global_load_lds_dwordx4 v135, s[28:29]
	s_add_i32 s45, s42, 0x12000
	v_lshl_add_u32 v137, v7, 12, v4
	s_mov_b32 m0, s45
	s_nop 0
	global_load_lds_dwordx4 v137, s[28:29]
	s_add_u32 s18, s28, 0x80000
	s_addc_u32 s19, s29, 0
	s_add_i32 s46, s42, 0x14000
	s_mov_b32 m0, s46
	s_nop 0
	global_load_lds_dwordx4 v135, s[18:19]
	s_add_i32 s47, s42, 0x16000
	s_mov_b32 m0, s47
	s_nop 0
	global_load_lds_dwordx4 v137, s[18:19]
	s_add_u32 s26, s38, s12
	s_addc_u32 s27, s39, s13
	s_mov_b32 m0, s42
	s_nop 0
	global_load_lds_dwordx4 v134, s[26:27]
	s_add_i32 s48, s42, 0x2000
	v_lshl_add_u32 v136, v6, 12, v4
	s_mov_b32 m0, s48
	s_nop 0
	global_load_lds_dwordx4 v136, s[26:27]
	s_add_u32 s18, s26, 0x80000
	s_addc_u32 s19, s27, 0
	s_add_i32 s49, s42, 0x4000
	s_mov_b32 m0, s49
	s_nop 0
	global_load_lds_dwordx4 v134, s[18:19]
	s_add_i32 s50, s42, 0x6000
	s_mov_b32 m0, s50
	s_nop 0
	global_load_lds_dwordx4 v136, s[18:19]
	s_cmp_eq_u32 s6, 1
	s_mov_b32 s43, 0
	s_cselect_b64 s[12:13], -1, 0
	s_cmp_lg_u32 s6, 1
	s_cbranch_scc1 .LBB0_2065
	s_barrier

;     __device__ bool next(int i, Unit& u) const {
;         const long L = (long)i * G + c; if (L >= nwg) return false;
;         int wgid = (int)L; { const int q = nwg / NXCD, r = nwg % NXCD, xcd = wgid % NXCD, off = wgid / NXCD; wgid = (xcd < r ? xcd * (q + 1) : r * (q + 1) + (xcd - r) * q) + off; }
;         const int nig = WGM * nN, gid = wgid / nig, fm = gid * WGM, gsz = (nM - fm) < WGM ? (nM - fm) : WGM;
;         u.pm = fm + ((wgid % nig) % gsz); u.pn = (wgid % nig) / gsz; return true;
.LBB0_2152:
	s_or_b64 exec, exec, s[4:5]
	s_mov_b64 s[4:5], s[0:1]
	s_mov_b64 s[8:9], s[0:1]
	s_mov_b64 s[6:7], s[0:1]
	s_mov_b64 s[2:3], s[0:1]
	s_waitcnt lgkmcnt(0)
	s_barrier
	v_readlane_b32 s99, v243, 40
	s_nop 1
	s_bitcmp1_b32 s99, 3
	s_cbranch_scc0 .Lstg_7
	s_sleep 18
.Lstg_7:
	s_mov_b64 s[10:11], s[0:1]
	v_readlane_b32 s2, v242, 18
	s_mov_b64 s[12:13], s[0:1]
	s_mov_b64 s[16:17], s[0:1]
	v_mov_b32_e32 v2, v0
	v_readlane_b32 s3, v242, 19
	s_and_b64 vcc, exec, s[2:3]
	v_readfirstlane_b32 s36, v2
	s_cbranch_vccnz .LBB0_2209
	s_load_dwordx2 s[22:23], s[4:5], 0xb0
	s_load_dwordx2 s[20:21], s[8:9], 0xb0
	s_lshr_b32 s2, s93, 29
	s_add_i32 s2, s92, s2
	s_and_b32 s3, s2, -8
	s_sub_i32 s8, s92, s3
	s_cmp_gt_i32 s8, -1
	s_cbranch_scc0 .LBB0_2155
	s_lshl_b32 s3, s8, 5
	s_cbranch_execz .LBB0_2156
	s_branch .LBB0_2157

; #define LAS __attribute__((address_space(3)))
; __device__ __forceinline__ int otid() { int t = threadIdx.x; asm volatile("" : "+v"(t)); return t; }
; __global__ void __launch_bounds__(NT, 2) fwd(Args args) {
;     extern __shared__ __attribute__((aligned(16))) unsigned char lds_raw[];
;     LAS unsigned char* lds = (LAS unsigned char*)lds_raw;
;     volatile LAS unsigned* MISC = (volatile LAS unsigned*)(lds + MISC_OFF);
;     const int tid = otid(), lane = tid & 63, wave = __builtin_amdgcn_readfirstlane(tid >> 6);
	.amdhsa_kernel _Z3fwd4Args
		.amdhsa_group_segment_fixed_size 0
		.amdhsa_private_segment_fixed_size 0
		.amdhsa_kernarg_size 440
		.amdhsa_user_sgpr_count 2
		.amdhsa_user_sgpr_dispatch_ptr 0
		.amdhsa_user_sgpr_queue_ptr 0
		.amdhsa_user_sgpr_kernarg_segment_ptr 1
		.amdhsa_user_sgpr_dispatch_id 0
		.amdhsa_user_sgpr_kernarg_preload_length 0
		.amdhsa_user_sgpr_kernarg_preload_offset 0
		.amdhsa_user_sgpr_private_segment_size 0
		.amdhsa_uses_dynamic_stack 0
		.amdhsa_enable_private_segment 0
		.amdhsa_system_sgpr_workgroup_id_x 1
		.amdhsa_system_sgpr_workgroup_id_y 0
		.amdhsa_system_sgpr_workgroup_id_z 0
		.amdhsa_system_sgpr_workgroup_info 0
		.amdhsa_system_vgpr_workitem_id 0
		.amdhsa_next_free_vgpr 244
		.amdhsa_next_free_sgpr 100
		.amdhsa_accum_offset 244
		.amdhsa_reserve_vcc 1
		.amdhsa_float_round_mode_32 0
		.amdhsa_float_round_mode_16_64 0
		.amdhsa_float_denorm_mode_32 3
		.amdhsa_float_denorm_mode_16_64 3
		.amdhsa_dx10_clamp 1
		.amdhsa_ieee_mode 1
		.amdhsa_fp16_overflow 0
		.amdhsa_tg_split 0
		.amdhsa_exception_fp_ieee_invalid_op 0
		.amdhsa_exception_fp_denorm_src 0
		.amdhsa_exception_fp_ieee_div_zero 0
		.amdhsa_exception_fp_ieee_overflow 0
		.amdhsa_exception_fp_ieee_underflow 0
		.amdhsa_exception_fp_ieee_inexact 0
		.amdhsa_exception_int_div_zero 0
	.end_amdhsa_kernel

; #define LAS __attribute__((address_space(3)))
; __device__ __forceinline__ int otid() { int t = threadIdx.x; asm volatile("" : "+v"(t)); return t; }
; __global__ void __launch_bounds__(NT, 2) fwd(Args args) {
;     extern __shared__ __attribute__((aligned(16))) unsigned char lds_raw[];
;     LAS unsigned char* lds = (LAS unsigned char*)lds_raw;
;     volatile LAS unsigned* MISC = (volatile LAS unsigned*)(lds + MISC_OFF);
;     const int tid = otid(), lane = tid & 63, wave = __builtin_amdgcn_readfirstlane(tid >> 6);
amdhsa.kernels:
  - .agpr_count:     0
    .args:
      - .offset:         0
        .size:           184
        .value_kind:     by_value
      - .offset:         184
        .size:           4
        .value_kind:     hidden_block_count_x
      - .offset:         188
        .size:           4
        .value_kind:     hidden_block_count_y
      - .offset:         192
        .size:           4
        .value_kind:     hidden_block_count_z
      - .offset:         196
        .size:           2
        .value_kind:     hidden_group_size_x
      - .offset:         198
        .size:           2
        .value_kind:     hidden_group_size_y
      - .offset:         200
        .size:           2
        .value_kind:     hidden_group_size_z
      - .offset:         202
        .size:           2
        .value_kind:     hidden_remainder_x
      - .offset:         204
        .size:           2
        .value_kind:     hidden_remainder_y
      - .offset:         206
        .size:           2
        .value_kind:     hidden_remainder_z
      - .offset:         224
        .size:           8
        .value_kind:     hidden_global_offset_x
      - .offset:         232
        .size:           8
        .value_kind:     hidden_global_offset_y
      - .offset:         240
        .size:           8
        .value_kind:     hidden_global_offset_z
      - .offset:         248
        .size:           2
        .value_kind:     hidden_grid_dims
      - .offset:         304
        .size:           4
        .value_kind:     hidden_dynamic_lds_size
    .group_segment_fixed_size: 0
    .kernarg_segment_align: 8
    .kernarg_segment_size: 440
    .language:       OpenCL C
    .language_version:
      - 2
      - 0
    .max_flat_workgroup_size: 512
    .name:           _Z3fwd4Args
    .private_segment_fixed_size: 0
    .sgpr_count:     106
    .sgpr_spill_count: 26
    .symbol:         _Z3fwd4Args.kd
    .uniform_work_group_size: 1
    .uses_dynamic_stack: false
    .vgpr_count:     244
    .vgpr_spill_count: 0
    .wavefront_size: 64
